# P0: weight-transpose loads issued 32 at a time, band K/V copy loads merged, adaLN GEMV weight loads prefetched one k-step ahead with plain FMA body
# speedup vs baseline: 1.0554x; 1.0095x over previous
.LBB0_35:
	s_andn2_b64 vcc, exec, s[28:29]
	s_cbranch_vccnz .Ltrc_zero
	v_add_u32_e32 v54, s6, v10
	v_ashrrev_i32_e32 v55, 31, v54
	v_lshlrev_b64 v[54:55], 13, v[54:55]
	v_lshl_add_u64 v[54:55], v[26:27], 0, v[54:55]
	global_load_dword v102, v[54:55], off
	v_add3_u32 v54, v10, s6, 2
	v_ashrrev_i32_e32 v55, 31, v54
	v_lshlrev_b64 v[54:55], 13, v[54:55]
	v_lshl_add_u64 v[54:55], v[26:27], 0, v[54:55]
	global_load_dword v103, v[54:55], off
	v_add3_u32 v54, v10, s6, 4
	v_ashrrev_i32_e32 v55, 31, v54
	v_lshlrev_b64 v[54:55], 13, v[54:55]
	v_lshl_add_u64 v[54:55], v[26:27], 0, v[54:55]
	global_load_dword v104, v[54:55], off
	v_add3_u32 v54, v10, s6, 6
	v_ashrrev_i32_e32 v55, 31, v54
	v_lshlrev_b64 v[54:55], 13, v[54:55]
	v_lshl_add_u64 v[54:55], v[26:27], 0, v[54:55]
	global_load_dword v105, v[54:55], off
	v_add3_u32 v54, v10, s6, 8
	v_ashrrev_i32_e32 v55, 31, v54
	v_lshlrev_b64 v[54:55], 13, v[54:55]
	v_lshl_add_u64 v[54:55], v[26:27], 0, v[54:55]
	global_load_dword v106, v[54:55], off
	v_add3_u32 v54, v10, s6, 10
	v_ashrrev_i32_e32 v55, 31, v54
	v_lshlrev_b64 v[54:55], 13, v[54:55]
	v_lshl_add_u64 v[54:55], v[26:27], 0, v[54:55]
	global_load_dword v107, v[54:55], off
	v_add3_u32 v54, v10, s6, 12
	v_ashrrev_i32_e32 v55, 31, v54
	v_lshlrev_b64 v[54:55], 13, v[54:55]
	v_lshl_add_u64 v[54:55], v[26:27], 0, v[54:55]
	global_load_dword v108, v[54:55], off
	v_add3_u32 v54, v10, s6, 14
	v_ashrrev_i32_e32 v55, 31, v54
	v_lshlrev_b64 v[54:55], 13, v[54:55]
	v_lshl_add_u64 v[54:55], v[26:27], 0, v[54:55]
	global_load_dword v109, v[54:55], off
	s_add_i32 s6, s6, 16
	v_add_u32_e32 v54, s6, v10
	v_ashrrev_i32_e32 v55, 31, v54
	v_lshlrev_b64 v[54:55], 13, v[54:55]
	v_lshl_add_u64 v[54:55], v[26:27], 0, v[54:55]
	global_load_dword v110, v[54:55], off
	v_add3_u32 v54, v10, s6, 2
	v_ashrrev_i32_e32 v55, 31, v54
	v_lshlrev_b64 v[54:55], 13, v[54:55]
	v_lshl_add_u64 v[54:55], v[26:27], 0, v[54:55]
	global_load_dword v111, v[54:55], off
	v_add3_u32 v54, v10, s6, 4
	v_ashrrev_i32_e32 v55, 31, v54
	v_lshlrev_b64 v[54:55], 13, v[54:55]
	v_lshl_add_u64 v[54:55], v[26:27], 0, v[54:55]
	global_load_dword v112, v[54:55], off
	v_add3_u32 v54, v10, s6, 6
	v_ashrrev_i32_e32 v55, 31, v54
	v_lshlrev_b64 v[54:55], 13, v[54:55]
	v_lshl_add_u64 v[54:55], v[26:27], 0, v[54:55]
	global_load_dword v113, v[54:55], off
	v_add3_u32 v54, v10, s6, 8
	v_ashrrev_i32_e32 v55, 31, v54
	v_lshlrev_b64 v[54:55], 13, v[54:55]
	v_lshl_add_u64 v[54:55], v[26:27], 0, v[54:55]
	global_load_dword v114, v[54:55], off
	v_add3_u32 v54, v10, s6, 10
	v_ashrrev_i32_e32 v55, 31, v54
	v_lshlrev_b64 v[54:55], 13, v[54:55]
	v_lshl_add_u64 v[54:55], v[26:27], 0, v[54:55]
	global_load_dword v115, v[54:55], off
	v_add3_u32 v54, v10, s6, 12
	v_ashrrev_i32_e32 v55, 31, v54
	v_lshlrev_b64 v[54:55], 13, v[54:55]
	v_lshl_add_u64 v[54:55], v[26:27], 0, v[54:55]
	global_load_dword v116, v[54:55], off
	v_add3_u32 v54, v10, s6, 14
	v_ashrrev_i32_e32 v55, 31, v54
	v_lshlrev_b64 v[54:55], 13, v[54:55]
	v_lshl_add_u64 v[54:55], v[26:27], 0, v[54:55]
	global_load_dword v117, v[54:55], off
	s_add_i32 s6, s6, 16
	v_add_u32_e32 v54, s6, v10
	v_ashrrev_i32_e32 v55, 31, v54
	v_lshlrev_b64 v[54:55], 13, v[54:55]
	v_lshl_add_u64 v[54:55], v[26:27], 0, v[54:55]
	global_load_dword v118, v[54:55], off
	v_add3_u32 v54, v10, s6, 2
	v_ashrrev_i32_e32 v55, 31, v54
	v_lshlrev_b64 v[54:55], 13, v[54:55]
	v_lshl_add_u64 v[54:55], v[26:27], 0, v[54:55]
	global_load_dword v119, v[54:55], off
	v_add3_u32 v54, v10, s6, 4
	v_ashrrev_i32_e32 v55, 31, v54
	v_lshlrev_b64 v[54:55], 13, v[54:55]
	v_lshl_add_u64 v[54:55], v[26:27], 0, v[54:55]
	global_load_dword v120, v[54:55], off
	v_add3_u32 v54, v10, s6, 6
	v_ashrrev_i32_e32 v55, 31, v54
	v_lshlrev_b64 v[54:55], 13, v[54:55]
	v_lshl_add_u64 v[54:55], v[26:27], 0, v[54:55]
	global_load_dword v121, v[54:55], off
	v_add3_u32 v54, v10, s6, 8
	v_ashrrev_i32_e32 v55, 31, v54
	v_lshlrev_b64 v[54:55], 13, v[54:55]
	v_lshl_add_u64 v[54:55], v[26:27], 0, v[54:55]
	global_load_dword v122, v[54:55], off
	v_add3_u32 v54, v10, s6, 10
	v_ashrrev_i32_e32 v55, 31, v54
	v_lshlrev_b64 v[54:55], 13, v[54:55]
	v_lshl_add_u64 v[54:55], v[26:27], 0, v[54:55]
	global_load_dword v123, v[54:55], off
	v_add3_u32 v54, v10, s6, 12
	v_ashrrev_i32_e32 v55, 31, v54
	v_lshlrev_b64 v[54:55], 13, v[54:55]
	v_lshl_add_u64 v[54:55], v[26:27], 0, v[54:55]
	global_load_dword v124, v[54:55], off
	v_add3_u32 v54, v10, s6, 14
	v_ashrrev_i32_e32 v55, 31, v54
	v_lshlrev_b64 v[54:55], 13, v[54:55]
	v_lshl_add_u64 v[54:55], v[26:27], 0, v[54:55]
	global_load_dword v125, v[54:55], off
	s_add_i32 s6, s6, 16
	v_add_u32_e32 v54, s6, v10
	v_ashrrev_i32_e32 v55, 31, v54
	v_lshlrev_b64 v[54:55], 13, v[54:55]
	v_lshl_add_u64 v[54:55], v[26:27], 0, v[54:55]
	global_load_dword v126, v[54:55], off
	v_add3_u32 v54, v10, s6, 2
	v_ashrrev_i32_e32 v55, 31, v54
	v_lshlrev_b64 v[54:55], 13, v[54:55]
	v_lshl_add_u64 v[54:55], v[26:27], 0, v[54:55]
	global_load_dword v127, v[54:55], off
	v_add3_u32 v54, v10, s6, 4
	v_ashrrev_i32_e32 v55, 31, v54
	v_lshlrev_b64 v[54:55], 13, v[54:55]
	v_lshl_add_u64 v[54:55], v[26:27], 0, v[54:55]
	global_load_dword v128, v[54:55], off
	v_add3_u32 v54, v10, s6, 6
	v_ashrrev_i32_e32 v55, 31, v54
	v_lshlrev_b64 v[54:55], 13, v[54:55]
	v_lshl_add_u64 v[54:55], v[26:27], 0, v[54:55]
	global_load_dword v129, v[54:55], off
	v_add3_u32 v54, v10, s6, 8
	v_ashrrev_i32_e32 v55, 31, v54
	v_lshlrev_b64 v[54:55], 13, v[54:55]
	v_lshl_add_u64 v[54:55], v[26:27], 0, v[54:55]
	global_load_dword v130, v[54:55], off
	v_add3_u32 v54, v10, s6, 10
	v_ashrrev_i32_e32 v55, 31, v54
	v_lshlrev_b64 v[54:55], 13, v[54:55]
	v_lshl_add_u64 v[54:55], v[26:27], 0, v[54:55]
	global_load_dword v131, v[54:55], off
	v_add3_u32 v54, v10, s6, 12
	v_ashrrev_i32_e32 v55, 31, v54
	v_lshlrev_b64 v[54:55], 13, v[54:55]
	v_lshl_add_u64 v[54:55], v[26:27], 0, v[54:55]
	global_load_dword v132, v[54:55], off
	v_add3_u32 v54, v10, s6, 14
	v_ashrrev_i32_e32 v55, 31, v54
	v_lshlrev_b64 v[54:55], 13, v[54:55]
	v_lshl_add_u64 v[54:55], v[26:27], 0, v[54:55]
	global_load_dword v133, v[54:55], off
	s_add_i32 s6, s6, 16
	s_branch .Ltrc_wr
.Ltrc_zero:
	v_mov_b32_e32 v102, 0
	v_mov_b32_e32 v103, 0
	v_mov_b32_e32 v104, 0
	v_mov_b32_e32 v105, 0
	v_mov_b32_e32 v106, 0
	v_mov_b32_e32 v107, 0
	v_mov_b32_e32 v108, 0
	v_mov_b32_e32 v109, 0
	v_mov_b32_e32 v110, 0
	v_mov_b32_e32 v111, 0
	v_mov_b32_e32 v112, 0
	v_mov_b32_e32 v113, 0
	v_mov_b32_e32 v114, 0
	v_mov_b32_e32 v115, 0
	v_mov_b32_e32 v116, 0
	v_mov_b32_e32 v117, 0
	v_mov_b32_e32 v118, 0
	v_mov_b32_e32 v119, 0
	v_mov_b32_e32 v120, 0
	v_mov_b32_e32 v121, 0
	v_mov_b32_e32 v122, 0
	v_mov_b32_e32 v123, 0
	v_mov_b32_e32 v124, 0
	v_mov_b32_e32 v125, 0
	v_mov_b32_e32 v126, 0
	v_mov_b32_e32 v127, 0
	v_mov_b32_e32 v128, 0
	v_mov_b32_e32 v129, 0
	v_mov_b32_e32 v130, 0
	v_mov_b32_e32 v131, 0
	v_mov_b32_e32 v132, 0
	v_mov_b32_e32 v133, 0
	s_add_i32 s6, s6, 16
	s_add_i32 s6, s6, 16
	s_add_i32 s6, s6, 16
	s_add_i32 s6, s6, 16
.Ltrc_wr:
	s_waitcnt vmcnt(31)
	ds_write_b32 v25, v102
	s_waitcnt vmcnt(30)
	ds_write_b32 v25, v103 offset:264
	s_waitcnt vmcnt(29)
	ds_write_b32 v25, v104 offset:528
	s_waitcnt vmcnt(28)
	ds_write_b32 v25, v105 offset:792
	s_waitcnt vmcnt(27)
	ds_write_b32 v25, v106 offset:1056
	s_waitcnt vmcnt(26)
	ds_write_b32 v25, v107 offset:1320
	s_waitcnt vmcnt(25)
	ds_write_b32 v25, v108 offset:1584
	s_waitcnt vmcnt(24)
	ds_write_b32 v25, v109 offset:1848
	s_waitcnt vmcnt(23)
	ds_write_b32 v25, v110 offset:2112
	s_waitcnt vmcnt(22)
	ds_write_b32 v25, v111 offset:2376
	s_waitcnt vmcnt(21)
	ds_write_b32 v25, v112 offset:2640
	s_waitcnt vmcnt(20)
	ds_write_b32 v25, v113 offset:2904
	s_waitcnt vmcnt(19)
	ds_write_b32 v25, v114 offset:3168
	s_waitcnt vmcnt(18)
	ds_write_b32 v25, v115 offset:3432
	s_waitcnt vmcnt(17)
	ds_write_b32 v25, v116 offset:3696
	s_waitcnt vmcnt(16)
	ds_write_b32 v25, v117 offset:3960
	s_waitcnt vmcnt(15)
	ds_write_b32 v25, v118 offset:4224
	s_waitcnt vmcnt(14)
	ds_write_b32 v25, v119 offset:4488
	s_waitcnt vmcnt(13)
	ds_write_b32 v25, v120 offset:4752
	s_waitcnt vmcnt(12)
	ds_write_b32 v25, v121 offset:5016
	s_waitcnt vmcnt(11)
	ds_write_b32 v25, v122 offset:5280
	s_waitcnt vmcnt(10)
	ds_write_b32 v25, v123 offset:5544
	s_waitcnt vmcnt(9)
	ds_write_b32 v25, v124 offset:5808
	s_waitcnt vmcnt(8)
	ds_write_b32 v25, v125 offset:6072
	s_waitcnt vmcnt(7)
	ds_write_b32 v25, v126 offset:6336
	s_waitcnt vmcnt(6)
	ds_write_b32 v25, v127 offset:6600
	s_waitcnt vmcnt(5)
	ds_write_b32 v25, v128 offset:6864
	s_waitcnt vmcnt(4)
	ds_write_b32 v25, v129 offset:7128
	s_waitcnt vmcnt(3)
	ds_write_b32 v25, v130 offset:7392
	s_waitcnt vmcnt(2)
	ds_write_b32 v25, v131 offset:7656
	s_waitcnt vmcnt(1)
	ds_write_b32 v25, v132 offset:7920
	s_waitcnt vmcnt(0)
	ds_write_b32 v25, v133 offset:8184
	s_branch .LBB0_51

.LBB0_77:
	s_andn2_b64 vcc, exec, s[28:29]
	s_cbranch_vccnz .Ltrb_zero
	v_lshl_add_u64 v[54:55], v[40:41], 0, s[30:31]
	global_load_dword v102, v[54:55], off
	v_lshl_add_u64 v[54:55], v[38:39], 0, s[30:31]
	global_load_dword v103, v[54:55], off
	v_lshl_add_u64 v[54:55], v[36:37], 0, s[30:31]
	global_load_dword v104, v[54:55], off
	v_lshl_add_u64 v[54:55], v[34:35], 0, s[30:31]
	global_load_dword v105, v[54:55], off
	v_lshl_add_u64 v[54:55], v[32:33], 0, s[30:31]
	global_load_dword v106, v[54:55], off
	v_lshl_add_u64 v[54:55], v[30:31], 0, s[30:31]
	global_load_dword v107, v[54:55], off
	v_lshl_add_u64 v[54:55], v[28:29], 0, s[30:31]
	global_load_dword v108, v[54:55], off
	v_lshl_add_u64 v[54:55], v[26:27], 0, s[30:31]
	global_load_dword v109, v[54:55], off
	s_add_u32 s30, s30, 0x1a800
	s_addc_u32 s31, s31, 0
	v_lshl_add_u64 v[54:55], v[40:41], 0, s[30:31]
	global_load_dword v110, v[54:55], off
	v_lshl_add_u64 v[54:55], v[38:39], 0, s[30:31]
	global_load_dword v111, v[54:55], off
	v_lshl_add_u64 v[54:55], v[36:37], 0, s[30:31]
	global_load_dword v112, v[54:55], off
	v_lshl_add_u64 v[54:55], v[34:35], 0, s[30:31]
	global_load_dword v113, v[54:55], off
	v_lshl_add_u64 v[54:55], v[32:33], 0, s[30:31]
	global_load_dword v114, v[54:55], off
	v_lshl_add_u64 v[54:55], v[30:31], 0, s[30:31]
	global_load_dword v115, v[54:55], off
	v_lshl_add_u64 v[54:55], v[28:29], 0, s[30:31]
	global_load_dword v116, v[54:55], off
	v_lshl_add_u64 v[54:55], v[26:27], 0, s[30:31]
	global_load_dword v117, v[54:55], off
	s_add_u32 s30, s30, 0x1a800
	s_addc_u32 s31, s31, 0
	v_lshl_add_u64 v[54:55], v[40:41], 0, s[30:31]
	global_load_dword v118, v[54:55], off
	v_lshl_add_u64 v[54:55], v[38:39], 0, s[30:31]
	global_load_dword v119, v[54:55], off
	v_lshl_add_u64 v[54:55], v[36:37], 0, s[30:31]
	global_load_dword v120, v[54:55], off
	v_lshl_add_u64 v[54:55], v[34:35], 0, s[30:31]
	global_load_dword v121, v[54:55], off
	v_lshl_add_u64 v[54:55], v[32:33], 0, s[30:31]
	global_load_dword v122, v[54:55], off
	v_lshl_add_u64 v[54:55], v[30:31], 0, s[30:31]
	global_load_dword v123, v[54:55], off
	v_lshl_add_u64 v[54:55], v[28:29], 0, s[30:31]
	global_load_dword v124, v[54:55], off
	v_lshl_add_u64 v[54:55], v[26:27], 0, s[30:31]
	global_load_dword v125, v[54:55], off
	s_add_u32 s30, s30, 0x1a800
	s_addc_u32 s31, s31, 0
	v_lshl_add_u64 v[54:55], v[40:41], 0, s[30:31]
	global_load_dword v126, v[54:55], off
	v_lshl_add_u64 v[54:55], v[38:39], 0, s[30:31]
	global_load_dword v127, v[54:55], off
	v_lshl_add_u64 v[54:55], v[36:37], 0, s[30:31]
	global_load_dword v128, v[54:55], off
	v_lshl_add_u64 v[54:55], v[34:35], 0, s[30:31]
	global_load_dword v129, v[54:55], off
	v_lshl_add_u64 v[54:55], v[32:33], 0, s[30:31]
	global_load_dword v130, v[54:55], off
	v_lshl_add_u64 v[54:55], v[30:31], 0, s[30:31]
	global_load_dword v131, v[54:55], off
	v_lshl_add_u64 v[54:55], v[28:29], 0, s[30:31]
	global_load_dword v132, v[54:55], off
	v_lshl_add_u64 v[54:55], v[26:27], 0, s[30:31]
	global_load_dword v133, v[54:55], off
	s_add_u32 s30, s30, 0x1a800
	s_addc_u32 s31, s31, 0
	s_branch .Ltrb_wr
.Ltrb_zero:
	v_mov_b32_e32 v102, 0
	v_mov_b32_e32 v103, 0
	v_mov_b32_e32 v104, 0
	v_mov_b32_e32 v105, 0
	v_mov_b32_e32 v106, 0
	v_mov_b32_e32 v107, 0
	v_mov_b32_e32 v108, 0
	v_mov_b32_e32 v109, 0
	v_mov_b32_e32 v110, 0
	v_mov_b32_e32 v111, 0
	v_mov_b32_e32 v112, 0
	v_mov_b32_e32 v113, 0
	v_mov_b32_e32 v114, 0
	v_mov_b32_e32 v115, 0
	v_mov_b32_e32 v116, 0
	v_mov_b32_e32 v117, 0
	v_mov_b32_e32 v118, 0
	v_mov_b32_e32 v119, 0
	v_mov_b32_e32 v120, 0
	v_mov_b32_e32 v121, 0
	v_mov_b32_e32 v122, 0
	v_mov_b32_e32 v123, 0
	v_mov_b32_e32 v124, 0
	v_mov_b32_e32 v125, 0
	v_mov_b32_e32 v126, 0
	v_mov_b32_e32 v127, 0
	v_mov_b32_e32 v128, 0
	v_mov_b32_e32 v129, 0
	v_mov_b32_e32 v130, 0
	v_mov_b32_e32 v131, 0
	v_mov_b32_e32 v132, 0
	v_mov_b32_e32 v133, 0
	s_add_u32 s30, s30, 0x1a800
	s_addc_u32 s31, s31, 0
	s_add_u32 s30, s30, 0x1a800
	s_addc_u32 s31, s31, 0
	s_add_u32 s30, s30, 0x1a800
	s_addc_u32 s31, s31, 0
	s_add_u32 s30, s30, 0x1a800
	s_addc_u32 s31, s31, 0
.Ltrb_wr:
	s_waitcnt vmcnt(31)
	ds_write_b32 v10, v102
	s_waitcnt vmcnt(30)
	ds_write_b32 v10, v103 offset:264
	s_waitcnt vmcnt(29)
	ds_write_b32 v10, v104 offset:528
	s_waitcnt vmcnt(28)
	ds_write_b32 v10, v105 offset:792
	s_waitcnt vmcnt(27)
	ds_write_b32 v10, v106 offset:1056
	s_waitcnt vmcnt(26)
	ds_write_b32 v10, v107 offset:1320
	s_waitcnt vmcnt(25)
	ds_write_b32 v10, v108 offset:1584
	s_waitcnt vmcnt(24)
	ds_write_b32 v10, v109 offset:1848
	s_waitcnt vmcnt(23)
	ds_write_b32 v10, v110 offset:2112
	s_waitcnt vmcnt(22)
	ds_write_b32 v10, v111 offset:2376
	s_waitcnt vmcnt(21)
	ds_write_b32 v10, v112 offset:2640
	s_waitcnt vmcnt(20)
	ds_write_b32 v10, v113 offset:2904
	s_waitcnt vmcnt(19)
	ds_write_b32 v10, v114 offset:3168
	s_waitcnt vmcnt(18)
	ds_write_b32 v10, v115 offset:3432
	s_waitcnt vmcnt(17)
	ds_write_b32 v10, v116 offset:3696
	s_waitcnt vmcnt(16)
	ds_write_b32 v10, v117 offset:3960
	s_waitcnt vmcnt(15)
	ds_write_b32 v10, v118 offset:4224
	s_waitcnt vmcnt(14)
	ds_write_b32 v10, v119 offset:4488
	s_waitcnt vmcnt(13)
	ds_write_b32 v10, v120 offset:4752
	s_waitcnt vmcnt(12)
	ds_write_b32 v10, v121 offset:5016
	s_waitcnt vmcnt(11)
	ds_write_b32 v10, v122 offset:5280
	s_waitcnt vmcnt(10)
	ds_write_b32 v10, v123 offset:5544
	s_waitcnt vmcnt(9)
	ds_write_b32 v10, v124 offset:5808
	s_waitcnt vmcnt(8)
	ds_write_b32 v10, v125 offset:6072
	s_waitcnt vmcnt(7)
	ds_write_b32 v10, v126 offset:6336
	s_waitcnt vmcnt(6)
	ds_write_b32 v10, v127 offset:6600
	s_waitcnt vmcnt(5)
	ds_write_b32 v10, v128 offset:6864
	s_waitcnt vmcnt(4)
	ds_write_b32 v10, v129 offset:7128
	s_waitcnt vmcnt(3)
	ds_write_b32 v10, v130 offset:7392
	s_waitcnt vmcnt(2)
	ds_write_b32 v10, v131 offset:7656
	s_waitcnt vmcnt(1)
	ds_write_b32 v10, v132 offset:7920
	s_waitcnt vmcnt(0)
	ds_write_b32 v10, v133 offset:8184
	s_branch .LBB0_93

.LBB0_102:
	s_andn2_b64 vcc, exec, s[30:31]
	s_cbranch_vccnz .Ltra_zero
	v_lshl_add_u64 v[54:55], v[40:41], 0, s[34:35]
	global_load_dword v102, v[54:55], off
	v_lshl_add_u64 v[54:55], v[38:39], 0, s[34:35]
	global_load_dword v103, v[54:55], off
	v_lshl_add_u64 v[54:55], v[36:37], 0, s[34:35]
	global_load_dword v104, v[54:55], off
	v_lshl_add_u64 v[54:55], v[34:35], 0, s[34:35]
	global_load_dword v105, v[54:55], off
	v_lshl_add_u64 v[54:55], v[32:33], 0, s[34:35]
	global_load_dword v106, v[54:55], off
	v_lshl_add_u64 v[54:55], v[30:31], 0, s[34:35]
	global_load_dword v107, v[54:55], off
	v_lshl_add_u64 v[54:55], v[28:29], 0, s[34:35]
	global_load_dword v108, v[54:55], off
	v_lshl_add_u64 v[54:55], v[26:27], 0, s[34:35]
	global_load_dword v109, v[54:55], off
	s_add_u32 s34, s34, 0x40000
	s_addc_u32 s35, s35, 0
	v_lshl_add_u64 v[54:55], v[40:41], 0, s[34:35]
	global_load_dword v110, v[54:55], off
	v_lshl_add_u64 v[54:55], v[38:39], 0, s[34:35]
	global_load_dword v111, v[54:55], off
	v_lshl_add_u64 v[54:55], v[36:37], 0, s[34:35]
	global_load_dword v112, v[54:55], off
	v_lshl_add_u64 v[54:55], v[34:35], 0, s[34:35]
	global_load_dword v113, v[54:55], off
	v_lshl_add_u64 v[54:55], v[32:33], 0, s[34:35]
	global_load_dword v114, v[54:55], off
	v_lshl_add_u64 v[54:55], v[30:31], 0, s[34:35]
	global_load_dword v115, v[54:55], off
	v_lshl_add_u64 v[54:55], v[28:29], 0, s[34:35]
	global_load_dword v116, v[54:55], off
	v_lshl_add_u64 v[54:55], v[26:27], 0, s[34:35]
	global_load_dword v117, v[54:55], off
	s_add_u32 s34, s34, 0x40000
	s_addc_u32 s35, s35, 0
	v_lshl_add_u64 v[54:55], v[40:41], 0, s[34:35]
	global_load_dword v118, v[54:55], off
	v_lshl_add_u64 v[54:55], v[38:39], 0, s[34:35]
	global_load_dword v119, v[54:55], off
	v_lshl_add_u64 v[54:55], v[36:37], 0, s[34:35]
	global_load_dword v120, v[54:55], off
	v_lshl_add_u64 v[54:55], v[34:35], 0, s[34:35]
	global_load_dword v121, v[54:55], off
	v_lshl_add_u64 v[54:55], v[32:33], 0, s[34:35]
	global_load_dword v122, v[54:55], off
	v_lshl_add_u64 v[54:55], v[30:31], 0, s[34:35]
	global_load_dword v123, v[54:55], off
	v_lshl_add_u64 v[54:55], v[28:29], 0, s[34:35]
	global_load_dword v124, v[54:55], off
	v_lshl_add_u64 v[54:55], v[26:27], 0, s[34:35]
	global_load_dword v125, v[54:55], off
	s_add_u32 s34, s34, 0x40000
	s_addc_u32 s35, s35, 0
	v_lshl_add_u64 v[54:55], v[40:41], 0, s[34:35]
	global_load_dword v126, v[54:55], off
	v_lshl_add_u64 v[54:55], v[38:39], 0, s[34:35]
	global_load_dword v127, v[54:55], off
	v_lshl_add_u64 v[54:55], v[36:37], 0, s[34:35]
	global_load_dword v128, v[54:55], off
	v_lshl_add_u64 v[54:55], v[34:35], 0, s[34:35]
	global_load_dword v129, v[54:55], off
	v_lshl_add_u64 v[54:55], v[32:33], 0, s[34:35]
	global_load_dword v130, v[54:55], off
	v_lshl_add_u64 v[54:55], v[30:31], 0, s[34:35]
	global_load_dword v131, v[54:55], off
	v_lshl_add_u64 v[54:55], v[28:29], 0, s[34:35]
	global_load_dword v132, v[54:55], off
	v_lshl_add_u64 v[54:55], v[26:27], 0, s[34:35]
	global_load_dword v133, v[54:55], off
	s_add_u32 s34, s34, 0x40000
	s_addc_u32 s35, s35, 0
	s_branch .Ltra_wr
.Ltra_zero:
	v_mov_b32_e32 v102, 0
	v_mov_b32_e32 v103, 0
	v_mov_b32_e32 v104, 0
	v_mov_b32_e32 v105, 0
	v_mov_b32_e32 v106, 0
	v_mov_b32_e32 v107, 0
	v_mov_b32_e32 v108, 0
	v_mov_b32_e32 v109, 0
	v_mov_b32_e32 v110, 0
	v_mov_b32_e32 v111, 0
	v_mov_b32_e32 v112, 0
	v_mov_b32_e32 v113, 0
	v_mov_b32_e32 v114, 0
	v_mov_b32_e32 v115, 0
	v_mov_b32_e32 v116, 0
	v_mov_b32_e32 v117, 0
	v_mov_b32_e32 v118, 0
	v_mov_b32_e32 v119, 0
	v_mov_b32_e32 v120, 0
	v_mov_b32_e32 v121, 0
	v_mov_b32_e32 v122, 0
	v_mov_b32_e32 v123, 0
	v_mov_b32_e32 v124, 0
	v_mov_b32_e32 v125, 0
	v_mov_b32_e32 v126, 0
	v_mov_b32_e32 v127, 0
	v_mov_b32_e32 v128, 0
	v_mov_b32_e32 v129, 0
	v_mov_b32_e32 v130, 0
	v_mov_b32_e32 v131, 0
	v_mov_b32_e32 v132, 0
	v_mov_b32_e32 v133, 0
	s_add_u32 s34, s34, 0x40000
	s_addc_u32 s35, s35, 0
	s_add_u32 s34, s34, 0x40000
	s_addc_u32 s35, s35, 0
	s_add_u32 s34, s34, 0x40000
	s_addc_u32 s35, s35, 0
	s_add_u32 s34, s34, 0x40000
	s_addc_u32 s35, s35, 0

.LBB0_121:
	s_xor_b64 s[34:35], s[36:37], -1
	s_add_i32 s36, s38, s11
	s_ashr_i32 s37, s36, 31
	s_load_dwordx2 s[56:57], s[26:27], 0x30
	s_load_dwordx2 s[58:59], s[26:27], 0x38
	v_lshl_add_u32 v52, s36, 2, v2
	s_waitcnt lgkmcnt(0)
	global_load_dword v64, v52, s[56:57]
	s_add_u32 s56, s56, 0x1000
	s_addc_u32 s57, s57, 0
	global_load_dword v65, v52, s[56:57]
	s_add_u32 s56, s56, 0x1000
	s_addc_u32 s57, s57, 0
	global_load_dword v66, v52, s[56:57]
	s_add_u32 s56, s56, 0x1000
	s_addc_u32 s57, s57, 0
	global_load_dword v67, v52, s[56:57]
	s_add_u32 s56, s56, 0x1000
	s_addc_u32 s57, s57, 0
	global_load_dword v68, v52, s[56:57]
	s_add_u32 s56, s56, 0x1000
	s_addc_u32 s57, s57, 0
	global_load_dword v69, v52, s[56:57]
	s_add_u32 s56, s56, 0x1000
	s_addc_u32 s57, s57, 0
	global_load_dword v70, v52, s[56:57]
	s_add_u32 s56, s56, 0x1000
	s_addc_u32 s57, s57, 0
	global_load_dword v71, v52, s[56:57]
	s_add_u32 s56, s56, 0x1000
	s_addc_u32 s57, s57, 0
	global_load_dword v72, v52, s[56:57]
	s_add_u32 s56, s56, 0x1000
	s_addc_u32 s57, s57, 0
	global_load_dword v73, v52, s[56:57]
	s_add_u32 s56, s56, 0x1000
	s_addc_u32 s57, s57, 0
	global_load_dword v74, v52, s[56:57]
	s_add_u32 s56, s56, 0x1000
	s_addc_u32 s57, s57, 0
	global_load_dword v75, v52, s[56:57]
	s_add_u32 s56, s56, 0x1000
	s_addc_u32 s57, s57, 0
	global_load_dword v76, v52, s[56:57]
	s_add_u32 s56, s56, 0x1000
	s_addc_u32 s57, s57, 0
	global_load_dword v77, v52, s[56:57]
	s_add_u32 s56, s56, 0x1000
	s_addc_u32 s57, s57, 0
	global_load_dword v78, v52, s[56:57]
	s_add_u32 s56, s56, 0x1000
	s_addc_u32 s57, s57, 0
	global_load_dword v79, v52, s[56:57]
	s_add_u32 s56, s56, 0x1000
	s_addc_u32 s57, s57, 0
	global_load_dword v80, v52, s[56:57]
	s_add_u32 s56, s56, 0x1000
	s_addc_u32 s57, s57, 0
	global_load_dword v81, v52, s[56:57]
	s_add_u32 s56, s56, 0x1000
	s_addc_u32 s57, s57, 0
	global_load_dword v82, v52, s[56:57]
	s_add_u32 s56, s56, 0x1000
	s_addc_u32 s57, s57, 0
	global_load_dword v83, v52, s[56:57]
	s_add_u32 s56, s56, 0x1000
	s_addc_u32 s57, s57, 0
	global_load_dword v84, v52, s[56:57]
	s_add_u32 s56, s56, 0x1000
	s_addc_u32 s57, s57, 0
	global_load_dword v85, v52, s[56:57]
	s_add_u32 s56, s56, 0x1000
	s_addc_u32 s57, s57, 0
	global_load_dword v86, v52, s[56:57]
	s_add_u32 s56, s56, 0x1000
	s_addc_u32 s57, s57, 0
	global_load_dword v87, v52, s[56:57]
	s_add_u32 s56, s56, 0x1000
	s_addc_u32 s57, s57, 0
	global_load_dword v88, v52, s[56:57]
	s_add_u32 s56, s56, 0x1000
	s_addc_u32 s57, s57, 0
	global_load_dword v89, v52, s[56:57]
	s_add_u32 s56, s56, 0x1000
	s_addc_u32 s57, s57, 0
	global_load_dword v90, v52, s[56:57]
	s_add_u32 s56, s56, 0x1000
	s_addc_u32 s57, s57, 0
	global_load_dword v91, v52, s[56:57]
	s_add_u32 s56, s56, 0x1000
	s_addc_u32 s57, s57, 0
	global_load_dword v92, v52, s[56:57]
	s_add_u32 s56, s56, 0x1000
	s_addc_u32 s57, s57, 0
	global_load_dword v93, v52, s[56:57]
	s_add_u32 s56, s56, 0x1000
	s_addc_u32 s57, s57, 0
	global_load_dword v94, v52, s[56:57]
	s_add_u32 s56, s56, 0x1000
	s_addc_u32 s57, s57, 0
	global_load_dword v95, v52, s[56:57]
	global_load_dword v96, v52, s[58:59]
	s_add_u32 s58, s58, 0x1000
	s_addc_u32 s59, s59, 0
	global_load_dword v97, v52, s[58:59]
	s_add_u32 s58, s58, 0x1000
	s_addc_u32 s59, s59, 0
	global_load_dword v98, v52, s[58:59]
	s_add_u32 s58, s58, 0x1000
	s_addc_u32 s59, s59, 0
	global_load_dword v99, v52, s[58:59]
	s_add_u32 s58, s58, 0x1000
	s_addc_u32 s59, s59, 0
	global_load_dword v100, v52, s[58:59]
	s_add_u32 s58, s58, 0x1000
	s_addc_u32 s59, s59, 0
	global_load_dword v101, v52, s[58:59]
	s_add_u32 s58, s58, 0x1000
	s_addc_u32 s59, s59, 0
	global_load_dword v102, v52, s[58:59]
	s_add_u32 s58, s58, 0x1000
	s_addc_u32 s59, s59, 0
	global_load_dword v103, v52, s[58:59]
	s_waitcnt vmcnt(39)
	v_mul_f32_e32 v104, 0xbfb8aa3b, v64
	v_exp_f32_e32 v104, v104
	s_nop 0
	v_add_f32_e32 v104, 1.0, v104
	v_div_scale_f32 v105, s[54:55], v104, v104, v64
	v_rcp_f32_e32 v106, v105
	v_div_scale_f32 v107, vcc, v64, v104, v64
	v_fma_f32 v108, -v105, v106, 1.0
	v_fmac_f32_e32 v106, v108, v106
	v_mul_f32_e32 v108, v107, v106
	v_fma_f32 v109, -v105, v108, v107
	v_fmac_f32_e32 v108, v109, v106
	v_fma_f32 v105, -v105, v108, v107
	v_div_fmas_f32 v105, v105, v106, v108
	v_div_fixup_f32 v64, v105, v104, v64
	ds_write_b32 v1, v64
	s_waitcnt vmcnt(38)
	v_mul_f32_e32 v104, 0xbfb8aa3b, v65
	v_exp_f32_e32 v104, v104
	s_nop 0
	v_add_f32_e32 v104, 1.0, v104
	v_div_scale_f32 v105, s[54:55], v104, v104, v65
	v_rcp_f32_e32 v106, v105
	v_div_scale_f32 v107, vcc, v65, v104, v65
	v_fma_f32 v108, -v105, v106, 1.0
	v_fmac_f32_e32 v106, v108, v106
	v_mul_f32_e32 v108, v107, v106
	v_fma_f32 v109, -v105, v108, v107
	v_fmac_f32_e32 v108, v109, v106
	v_fma_f32 v105, -v105, v108, v107
	v_div_fmas_f32 v105, v105, v106, v108
	v_div_fixup_f32 v65, v105, v104, v65
	ds_write_b32 v1, v65 offset:256
	s_waitcnt vmcnt(37)
	v_mul_f32_e32 v104, 0xbfb8aa3b, v66
	v_exp_f32_e32 v104, v104
	s_nop 0
	v_add_f32_e32 v104, 1.0, v104
	v_div_scale_f32 v105, s[54:55], v104, v104, v66
	v_rcp_f32_e32 v106, v105
	v_div_scale_f32 v107, vcc, v66, v104, v66
	v_fma_f32 v108, -v105, v106, 1.0
	v_fmac_f32_e32 v106, v108, v106
	v_mul_f32_e32 v108, v107, v106
	v_fma_f32 v109, -v105, v108, v107
	v_fmac_f32_e32 v108, v109, v106
	v_fma_f32 v105, -v105, v108, v107
	v_div_fmas_f32 v105, v105, v106, v108
	v_div_fixup_f32 v66, v105, v104, v66
	ds_write_b32 v1, v66 offset:512
	s_waitcnt vmcnt(36)
	v_mul_f32_e32 v104, 0xbfb8aa3b, v67
	v_exp_f32_e32 v104, v104
	s_nop 0
	v_add_f32_e32 v104, 1.0, v104
	v_div_scale_f32 v105, s[54:55], v104, v104, v67
	v_rcp_f32_e32 v106, v105
	v_div_scale_f32 v107, vcc, v67, v104, v67
	v_fma_f32 v108, -v105, v106, 1.0
	v_fmac_f32_e32 v106, v108, v106
	v_mul_f32_e32 v108, v107, v106
	v_fma_f32 v109, -v105, v108, v107
	v_fmac_f32_e32 v108, v109, v106
	v_fma_f32 v105, -v105, v108, v107
	v_div_fmas_f32 v105, v105, v106, v108
	v_div_fixup_f32 v67, v105, v104, v67
	ds_write_b32 v1, v67 offset:768
	s_waitcnt vmcnt(35)
	v_mul_f32_e32 v104, 0xbfb8aa3b, v68
	v_exp_f32_e32 v104, v104
	s_nop 0
	v_add_f32_e32 v104, 1.0, v104
	v_div_scale_f32 v105, s[54:55], v104, v104, v68
	v_rcp_f32_e32 v106, v105
	v_div_scale_f32 v107, vcc, v68, v104, v68
	v_fma_f32 v108, -v105, v106, 1.0
	v_fmac_f32_e32 v106, v108, v106
	v_mul_f32_e32 v108, v107, v106
	v_fma_f32 v109, -v105, v108, v107
	v_fmac_f32_e32 v108, v109, v106
	v_fma_f32 v105, -v105, v108, v107
	v_div_fmas_f32 v105, v105, v106, v108
	v_div_fixup_f32 v68, v105, v104, v68
	ds_write_b32 v1, v68 offset:1024
	s_waitcnt vmcnt(34)
	v_mul_f32_e32 v104, 0xbfb8aa3b, v69
	v_exp_f32_e32 v104, v104
	s_nop 0
	v_add_f32_e32 v104, 1.0, v104
	v_div_scale_f32 v105, s[54:55], v104, v104, v69
	v_rcp_f32_e32 v106, v105
	v_div_scale_f32 v107, vcc, v69, v104, v69
	v_fma_f32 v108, -v105, v106, 1.0
	v_fmac_f32_e32 v106, v108, v106
	v_mul_f32_e32 v108, v107, v106
	v_fma_f32 v109, -v105, v108, v107
	v_fmac_f32_e32 v108, v109, v106
	v_fma_f32 v105, -v105, v108, v107
	v_div_fmas_f32 v105, v105, v106, v108
	v_div_fixup_f32 v69, v105, v104, v69
	ds_write_b32 v1, v69 offset:1280
	s_waitcnt vmcnt(33)
	v_mul_f32_e32 v104, 0xbfb8aa3b, v70
	v_exp_f32_e32 v104, v104
	s_nop 0
	v_add_f32_e32 v104, 1.0, v104
	v_div_scale_f32 v105, s[54:55], v104, v104, v70
	v_rcp_f32_e32 v106, v105
	v_div_scale_f32 v107, vcc, v70, v104, v70
	v_fma_f32 v108, -v105, v106, 1.0
	v_fmac_f32_e32 v106, v108, v106
	v_mul_f32_e32 v108, v107, v106
	v_fma_f32 v109, -v105, v108, v107
	v_fmac_f32_e32 v108, v109, v106
	v_fma_f32 v105, -v105, v108, v107
	v_div_fmas_f32 v105, v105, v106, v108
	v_div_fixup_f32 v70, v105, v104, v70
	ds_write_b32 v1, v70 offset:1536
	s_waitcnt vmcnt(32)
	v_mul_f32_e32 v104, 0xbfb8aa3b, v71
	v_exp_f32_e32 v104, v104
	s_nop 0
	v_add_f32_e32 v104, 1.0, v104
	v_div_scale_f32 v105, s[54:55], v104, v104, v71
	v_rcp_f32_e32 v106, v105
	v_div_scale_f32 v107, vcc, v71, v104, v71
	v_fma_f32 v108, -v105, v106, 1.0
	v_fmac_f32_e32 v106, v108, v106
	v_mul_f32_e32 v108, v107, v106
	v_fma_f32 v109, -v105, v108, v107
	v_fmac_f32_e32 v108, v109, v106
	v_fma_f32 v105, -v105, v108, v107
	v_div_fmas_f32 v105, v105, v106, v108
	v_div_fixup_f32 v71, v105, v104, v71
	ds_write_b32 v1, v71 offset:1792
	s_waitcnt vmcnt(31)
	v_mul_f32_e32 v104, 0xbfb8aa3b, v72
	v_exp_f32_e32 v104, v104
	s_nop 0
	v_add_f32_e32 v104, 1.0, v104
	v_div_scale_f32 v105, s[54:55], v104, v104, v72
	v_rcp_f32_e32 v106, v105
	v_div_scale_f32 v107, vcc, v72, v104, v72
	v_fma_f32 v108, -v105, v106, 1.0
	v_fmac_f32_e32 v106, v108, v106
	v_mul_f32_e32 v108, v107, v106
	v_fma_f32 v109, -v105, v108, v107
	v_fmac_f32_e32 v108, v109, v106
	v_fma_f32 v105, -v105, v108, v107
	v_div_fmas_f32 v105, v105, v106, v108
	v_div_fixup_f32 v72, v105, v104, v72
	ds_write_b32 v1, v72 offset:2048
	s_waitcnt vmcnt(30)
	v_mul_f32_e32 v104, 0xbfb8aa3b, v73
	v_exp_f32_e32 v104, v104
	s_nop 0
	v_add_f32_e32 v104, 1.0, v104
	v_div_scale_f32 v105, s[54:55], v104, v104, v73
	v_rcp_f32_e32 v106, v105
	v_div_scale_f32 v107, vcc, v73, v104, v73
	v_fma_f32 v108, -v105, v106, 1.0
	v_fmac_f32_e32 v106, v108, v106
	v_mul_f32_e32 v108, v107, v106
	v_fma_f32 v109, -v105, v108, v107
	v_fmac_f32_e32 v108, v109, v106
	v_fma_f32 v105, -v105, v108, v107
	v_div_fmas_f32 v105, v105, v106, v108
	v_div_fixup_f32 v73, v105, v104, v73
	ds_write_b32 v1, v73 offset:2304
	s_waitcnt vmcnt(29)
	v_mul_f32_e32 v104, 0xbfb8aa3b, v74
	v_exp_f32_e32 v104, v104
	s_nop 0
	v_add_f32_e32 v104, 1.0, v104
	v_div_scale_f32 v105, s[54:55], v104, v104, v74
	v_rcp_f32_e32 v106, v105
	v_div_scale_f32 v107, vcc, v74, v104, v74
	v_fma_f32 v108, -v105, v106, 1.0
	v_fmac_f32_e32 v106, v108, v106
	v_mul_f32_e32 v108, v107, v106
	v_fma_f32 v109, -v105, v108, v107
	v_fmac_f32_e32 v108, v109, v106
	v_fma_f32 v105, -v105, v108, v107
	v_div_fmas_f32 v105, v105, v106, v108
	v_div_fixup_f32 v74, v105, v104, v74
	ds_write_b32 v1, v74 offset:2560
	s_waitcnt vmcnt(28)
	v_mul_f32_e32 v104, 0xbfb8aa3b, v75
	v_exp_f32_e32 v104, v104
	s_nop 0
	v_add_f32_e32 v104, 1.0, v104
	v_div_scale_f32 v105, s[54:55], v104, v104, v75
	v_rcp_f32_e32 v106, v105
	v_div_scale_f32 v107, vcc, v75, v104, v75
	v_fma_f32 v108, -v105, v106, 1.0
	v_fmac_f32_e32 v106, v108, v106
	v_mul_f32_e32 v108, v107, v106
	v_fma_f32 v109, -v105, v108, v107
	v_fmac_f32_e32 v108, v109, v106
	v_fma_f32 v105, -v105, v108, v107
	v_div_fmas_f32 v105, v105, v106, v108
	v_div_fixup_f32 v75, v105, v104, v75
	ds_write_b32 v1, v75 offset:2816
	s_waitcnt vmcnt(27)
	v_mul_f32_e32 v104, 0xbfb8aa3b, v76
	v_exp_f32_e32 v104, v104
	s_nop 0
	v_add_f32_e32 v104, 1.0, v104
	v_div_scale_f32 v105, s[54:55], v104, v104, v76
	v_rcp_f32_e32 v106, v105
	v_div_scale_f32 v107, vcc, v76, v104, v76
	v_fma_f32 v108, -v105, v106, 1.0
	v_fmac_f32_e32 v106, v108, v106
	v_mul_f32_e32 v108, v107, v106
	v_fma_f32 v109, -v105, v108, v107
	v_fmac_f32_e32 v108, v109, v106
	v_fma_f32 v105, -v105, v108, v107
	v_div_fmas_f32 v105, v105, v106, v108
	v_div_fixup_f32 v76, v105, v104, v76
	ds_write_b32 v1, v76 offset:3072
	s_waitcnt vmcnt(26)
	v_mul_f32_e32 v104, 0xbfb8aa3b, v77
	v_exp_f32_e32 v104, v104
	s_nop 0
	v_add_f32_e32 v104, 1.0, v104
	v_div_scale_f32 v105, s[54:55], v104, v104, v77
	v_rcp_f32_e32 v106, v105
	v_div_scale_f32 v107, vcc, v77, v104, v77
	v_fma_f32 v108, -v105, v106, 1.0
	v_fmac_f32_e32 v106, v108, v106
	v_mul_f32_e32 v108, v107, v106
	v_fma_f32 v109, -v105, v108, v107
	v_fmac_f32_e32 v108, v109, v106
	v_fma_f32 v105, -v105, v108, v107
	v_div_fmas_f32 v105, v105, v106, v108
	v_div_fixup_f32 v77, v105, v104, v77
	ds_write_b32 v1, v77 offset:3328
	s_waitcnt vmcnt(25)
	v_mul_f32_e32 v104, 0xbfb8aa3b, v78
	v_exp_f32_e32 v104, v104
	s_nop 0
	v_add_f32_e32 v104, 1.0, v104
	v_div_scale_f32 v105, s[54:55], v104, v104, v78
	v_rcp_f32_e32 v106, v105
	v_div_scale_f32 v107, vcc, v78, v104, v78
	v_fma_f32 v108, -v105, v106, 1.0
	v_fmac_f32_e32 v106, v108, v106
	v_mul_f32_e32 v108, v107, v106
	v_fma_f32 v109, -v105, v108, v107
	v_fmac_f32_e32 v108, v109, v106
	v_fma_f32 v105, -v105, v108, v107
	v_div_fmas_f32 v105, v105, v106, v108
	v_div_fixup_f32 v78, v105, v104, v78
	ds_write_b32 v1, v78 offset:3584
	s_waitcnt vmcnt(24)
	v_mul_f32_e32 v104, 0xbfb8aa3b, v79
	v_exp_f32_e32 v104, v104
	s_nop 0
	v_add_f32_e32 v104, 1.0, v104
	v_div_scale_f32 v105, s[54:55], v104, v104, v79
	v_rcp_f32_e32 v106, v105
	v_div_scale_f32 v107, vcc, v79, v104, v79
	v_fma_f32 v108, -v105, v106, 1.0
	v_fmac_f32_e32 v106, v108, v106
	v_mul_f32_e32 v108, v107, v106
	v_fma_f32 v109, -v105, v108, v107
	v_fmac_f32_e32 v108, v109, v106
	v_fma_f32 v105, -v105, v108, v107
	v_div_fmas_f32 v105, v105, v106, v108
	v_div_fixup_f32 v79, v105, v104, v79
	ds_write_b32 v1, v79 offset:3840
	s_waitcnt vmcnt(23)
	v_mul_f32_e32 v104, 0xbfb8aa3b, v80
	v_exp_f32_e32 v104, v104
	s_nop 0
	v_add_f32_e32 v104, 1.0, v104
	v_div_scale_f32 v105, s[54:55], v104, v104, v80
	v_rcp_f32_e32 v106, v105
	v_div_scale_f32 v107, vcc, v80, v104, v80
	v_fma_f32 v108, -v105, v106, 1.0
	v_fmac_f32_e32 v106, v108, v106
	v_mul_f32_e32 v108, v107, v106
	v_fma_f32 v109, -v105, v108, v107
	v_fmac_f32_e32 v108, v109, v106
	v_fma_f32 v105, -v105, v108, v107
	v_div_fmas_f32 v105, v105, v106, v108
	v_div_fixup_f32 v80, v105, v104, v80
	ds_write_b32 v1, v80 offset:4096
	s_waitcnt vmcnt(22)
	v_mul_f32_e32 v104, 0xbfb8aa3b, v81
	v_exp_f32_e32 v104, v104
	s_nop 0
	v_add_f32_e32 v104, 1.0, v104
	v_div_scale_f32 v105, s[54:55], v104, v104, v81
	v_rcp_f32_e32 v106, v105
	v_div_scale_f32 v107, vcc, v81, v104, v81
	v_fma_f32 v108, -v105, v106, 1.0
	v_fmac_f32_e32 v106, v108, v106
	v_mul_f32_e32 v108, v107, v106
	v_fma_f32 v109, -v105, v108, v107
	v_fmac_f32_e32 v108, v109, v106
	v_fma_f32 v105, -v105, v108, v107
	v_div_fmas_f32 v105, v105, v106, v108
	v_div_fixup_f32 v81, v105, v104, v81
	ds_write_b32 v1, v81 offset:4352
	s_waitcnt vmcnt(21)
	v_mul_f32_e32 v104, 0xbfb8aa3b, v82
	v_exp_f32_e32 v104, v104
	s_nop 0
	v_add_f32_e32 v104, 1.0, v104
	v_div_scale_f32 v105, s[54:55], v104, v104, v82
	v_rcp_f32_e32 v106, v105
	v_div_scale_f32 v107, vcc, v82, v104, v82
	v_fma_f32 v108, -v105, v106, 1.0
	v_fmac_f32_e32 v106, v108, v106
	v_mul_f32_e32 v108, v107, v106
	v_fma_f32 v109, -v105, v108, v107
	v_fmac_f32_e32 v108, v109, v106
	v_fma_f32 v105, -v105, v108, v107
	v_div_fmas_f32 v105, v105, v106, v108
	v_div_fixup_f32 v82, v105, v104, v82
	ds_write_b32 v1, v82 offset:4608
	s_waitcnt vmcnt(20)
	v_mul_f32_e32 v104, 0xbfb8aa3b, v83
	v_exp_f32_e32 v104, v104
	s_nop 0
	v_add_f32_e32 v104, 1.0, v104
	v_div_scale_f32 v105, s[54:55], v104, v104, v83
	v_rcp_f32_e32 v106, v105
	v_div_scale_f32 v107, vcc, v83, v104, v83
	v_fma_f32 v108, -v105, v106, 1.0
	v_fmac_f32_e32 v106, v108, v106
	v_mul_f32_e32 v108, v107, v106
	v_fma_f32 v109, -v105, v108, v107
	v_fmac_f32_e32 v108, v109, v106
	v_fma_f32 v105, -v105, v108, v107
	v_div_fmas_f32 v105, v105, v106, v108
	v_div_fixup_f32 v83, v105, v104, v83
	ds_write_b32 v1, v83 offset:4864
	s_waitcnt vmcnt(19)
	v_mul_f32_e32 v104, 0xbfb8aa3b, v84
	v_exp_f32_e32 v104, v104
	s_nop 0
	v_add_f32_e32 v104, 1.0, v104
	v_div_scale_f32 v105, s[54:55], v104, v104, v84
	v_rcp_f32_e32 v106, v105
	v_div_scale_f32 v107, vcc, v84, v104, v84
	v_fma_f32 v108, -v105, v106, 1.0
	v_fmac_f32_e32 v106, v108, v106
	v_mul_f32_e32 v108, v107, v106
	v_fma_f32 v109, -v105, v108, v107
	v_fmac_f32_e32 v108, v109, v106
	v_fma_f32 v105, -v105, v108, v107
	v_div_fmas_f32 v105, v105, v106, v108
	v_div_fixup_f32 v84, v105, v104, v84
	ds_write_b32 v1, v84 offset:5120
	s_waitcnt vmcnt(18)
	v_mul_f32_e32 v104, 0xbfb8aa3b, v85
	v_exp_f32_e32 v104, v104
	s_nop 0
	v_add_f32_e32 v104, 1.0, v104
	v_div_scale_f32 v105, s[54:55], v104, v104, v85
	v_rcp_f32_e32 v106, v105
	v_div_scale_f32 v107, vcc, v85, v104, v85
	v_fma_f32 v108, -v105, v106, 1.0
	v_fmac_f32_e32 v106, v108, v106
	v_mul_f32_e32 v108, v107, v106
	v_fma_f32 v109, -v105, v108, v107
	v_fmac_f32_e32 v108, v109, v106
	v_fma_f32 v105, -v105, v108, v107
	v_div_fmas_f32 v105, v105, v106, v108
	v_div_fixup_f32 v85, v105, v104, v85
	ds_write_b32 v1, v85 offset:5376
	s_waitcnt vmcnt(17)
	v_mul_f32_e32 v104, 0xbfb8aa3b, v86
	v_exp_f32_e32 v104, v104
	s_nop 0
	v_add_f32_e32 v104, 1.0, v104
	v_div_scale_f32 v105, s[54:55], v104, v104, v86
	v_rcp_f32_e32 v106, v105
	v_div_scale_f32 v107, vcc, v86, v104, v86
	v_fma_f32 v108, -v105, v106, 1.0
	v_fmac_f32_e32 v106, v108, v106
	v_mul_f32_e32 v108, v107, v106
	v_fma_f32 v109, -v105, v108, v107
	v_fmac_f32_e32 v108, v109, v106
	v_fma_f32 v105, -v105, v108, v107
	v_div_fmas_f32 v105, v105, v106, v108
	v_div_fixup_f32 v86, v105, v104, v86
	ds_write_b32 v1, v86 offset:5632
	s_waitcnt vmcnt(16)
	v_mul_f32_e32 v104, 0xbfb8aa3b, v87
	v_exp_f32_e32 v104, v104
	s_nop 0
	v_add_f32_e32 v104, 1.0, v104
	v_div_scale_f32 v105, s[54:55], v104, v104, v87
	v_rcp_f32_e32 v106, v105
	v_div_scale_f32 v107, vcc, v87, v104, v87
	v_fma_f32 v108, -v105, v106, 1.0
	v_fmac_f32_e32 v106, v108, v106
	v_mul_f32_e32 v108, v107, v106
	v_fma_f32 v109, -v105, v108, v107
	v_fmac_f32_e32 v108, v109, v106
	v_fma_f32 v105, -v105, v108, v107
	v_div_fmas_f32 v105, v105, v106, v108
	v_div_fixup_f32 v87, v105, v104, v87
	ds_write_b32 v1, v87 offset:5888
	s_waitcnt vmcnt(15)
	v_mul_f32_e32 v104, 0xbfb8aa3b, v88
	v_exp_f32_e32 v104, v104
	s_nop 0
	v_add_f32_e32 v104, 1.0, v104
	v_div_scale_f32 v105, s[54:55], v104, v104, v88
	v_rcp_f32_e32 v106, v105
	v_div_scale_f32 v107, vcc, v88, v104, v88
	v_fma_f32 v108, -v105, v106, 1.0
	v_fmac_f32_e32 v106, v108, v106
	v_mul_f32_e32 v108, v107, v106
	v_fma_f32 v109, -v105, v108, v107
	v_fmac_f32_e32 v108, v109, v106
	v_fma_f32 v105, -v105, v108, v107
	v_div_fmas_f32 v105, v105, v106, v108
	v_div_fixup_f32 v88, v105, v104, v88
	ds_write_b32 v1, v88 offset:6144
	s_waitcnt vmcnt(14)
	v_mul_f32_e32 v104, 0xbfb8aa3b, v89
	v_exp_f32_e32 v104, v104
	s_nop 0
	v_add_f32_e32 v104, 1.0, v104
	v_div_scale_f32 v105, s[54:55], v104, v104, v89
	v_rcp_f32_e32 v106, v105
	v_div_scale_f32 v107, vcc, v89, v104, v89
	v_fma_f32 v108, -v105, v106, 1.0
	v_fmac_f32_e32 v106, v108, v106
	v_mul_f32_e32 v108, v107, v106
	v_fma_f32 v109, -v105, v108, v107
	v_fmac_f32_e32 v108, v109, v106
	v_fma_f32 v105, -v105, v108, v107
	v_div_fmas_f32 v105, v105, v106, v108
	v_div_fixup_f32 v89, v105, v104, v89
	ds_write_b32 v1, v89 offset:6400
	s_waitcnt vmcnt(13)
	v_mul_f32_e32 v104, 0xbfb8aa3b, v90
	v_exp_f32_e32 v104, v104
	s_nop 0
	v_add_f32_e32 v104, 1.0, v104
	v_div_scale_f32 v105, s[54:55], v104, v104, v90
	v_rcp_f32_e32 v106, v105
	v_div_scale_f32 v107, vcc, v90, v104, v90
	v_fma_f32 v108, -v105, v106, 1.0
	v_fmac_f32_e32 v106, v108, v106
	v_mul_f32_e32 v108, v107, v106
	v_fma_f32 v109, -v105, v108, v107
	v_fmac_f32_e32 v108, v109, v106
	v_fma_f32 v105, -v105, v108, v107
	v_div_fmas_f32 v105, v105, v106, v108
	v_div_fixup_f32 v90, v105, v104, v90
	ds_write_b32 v1, v90 offset:6656
	s_waitcnt vmcnt(12)
	v_mul_f32_e32 v104, 0xbfb8aa3b, v91
	v_exp_f32_e32 v104, v104
	s_nop 0
	v_add_f32_e32 v104, 1.0, v104
	v_div_scale_f32 v105, s[54:55], v104, v104, v91
	v_rcp_f32_e32 v106, v105
	v_div_scale_f32 v107, vcc, v91, v104, v91
	v_fma_f32 v108, -v105, v106, 1.0
	v_fmac_f32_e32 v106, v108, v106
	v_mul_f32_e32 v108, v107, v106
	v_fma_f32 v109, -v105, v108, v107
	v_fmac_f32_e32 v108, v109, v106
	v_fma_f32 v105, -v105, v108, v107
	v_div_fmas_f32 v105, v105, v106, v108
	v_div_fixup_f32 v91, v105, v104, v91
	ds_write_b32 v1, v91 offset:6912
	s_waitcnt vmcnt(11)
	v_mul_f32_e32 v104, 0xbfb8aa3b, v92
	v_exp_f32_e32 v104, v104
	s_nop 0
	v_add_f32_e32 v104, 1.0, v104
	v_div_scale_f32 v105, s[54:55], v104, v104, v92
	v_rcp_f32_e32 v106, v105
	v_div_scale_f32 v107, vcc, v92, v104, v92
	v_fma_f32 v108, -v105, v106, 1.0
	v_fmac_f32_e32 v106, v108, v106
	v_mul_f32_e32 v108, v107, v106
	v_fma_f32 v109, -v105, v108, v107
	v_fmac_f32_e32 v108, v109, v106
	v_fma_f32 v105, -v105, v108, v107
	v_div_fmas_f32 v105, v105, v106, v108
	v_div_fixup_f32 v92, v105, v104, v92
	ds_write_b32 v1, v92 offset:7168
	s_waitcnt vmcnt(10)
	v_mul_f32_e32 v104, 0xbfb8aa3b, v93
	v_exp_f32_e32 v104, v104
	s_nop 0
	v_add_f32_e32 v104, 1.0, v104
	v_div_scale_f32 v105, s[54:55], v104, v104, v93
	v_rcp_f32_e32 v106, v105
	v_div_scale_f32 v107, vcc, v93, v104, v93
	v_fma_f32 v108, -v105, v106, 1.0
	v_fmac_f32_e32 v106, v108, v106
	v_mul_f32_e32 v108, v107, v106
	v_fma_f32 v109, -v105, v108, v107
	v_fmac_f32_e32 v108, v109, v106
	v_fma_f32 v105, -v105, v108, v107
	v_div_fmas_f32 v105, v105, v106, v108
	v_div_fixup_f32 v93, v105, v104, v93
	ds_write_b32 v1, v93 offset:7424
	s_waitcnt vmcnt(9)
	v_mul_f32_e32 v104, 0xbfb8aa3b, v94
	v_exp_f32_e32 v104, v104
	s_nop 0
	v_add_f32_e32 v104, 1.0, v104
	v_div_scale_f32 v105, s[54:55], v104, v104, v94
	v_rcp_f32_e32 v106, v105
	v_div_scale_f32 v107, vcc, v94, v104, v94
	v_fma_f32 v108, -v105, v106, 1.0
	v_fmac_f32_e32 v106, v108, v106
	v_mul_f32_e32 v108, v107, v106
	v_fma_f32 v109, -v105, v108, v107
	v_fmac_f32_e32 v108, v109, v106
	v_fma_f32 v105, -v105, v108, v107
	v_div_fmas_f32 v105, v105, v106, v108
	v_div_fixup_f32 v94, v105, v104, v94
	ds_write_b32 v1, v94 offset:7680
	s_waitcnt vmcnt(8)
	v_mul_f32_e32 v104, 0xbfb8aa3b, v95
	v_exp_f32_e32 v104, v104
	s_nop 0
	v_add_f32_e32 v104, 1.0, v104
	v_div_scale_f32 v105, s[54:55], v104, v104, v95
	v_rcp_f32_e32 v106, v105
	v_div_scale_f32 v107, vcc, v95, v104, v95
	v_fma_f32 v108, -v105, v106, 1.0
	v_fmac_f32_e32 v106, v108, v106
	v_mul_f32_e32 v108, v107, v106
	v_fma_f32 v109, -v105, v108, v107
	v_fmac_f32_e32 v108, v109, v106
	v_fma_f32 v105, -v105, v108, v107
	v_div_fmas_f32 v105, v105, v106, v108
	v_div_fixup_f32 v95, v105, v104, v95
	ds_write_b32 v1, v95 offset:7936
	s_waitcnt vmcnt(7)
	v_mul_f32_e32 v104, 0xbfb8aa3b, v96
	v_exp_f32_e32 v104, v104
	s_nop 0
	v_add_f32_e32 v104, 1.0, v104
	v_div_scale_f32 v105, s[54:55], v104, v104, v96
	v_rcp_f32_e32 v106, v105
	v_div_scale_f32 v107, vcc, v96, v104, v96
	v_fma_f32 v108, -v105, v106, 1.0
	v_fmac_f32_e32 v106, v108, v106
	v_mul_f32_e32 v108, v107, v106
	v_fma_f32 v109, -v105, v108, v107
	v_fmac_f32_e32 v108, v109, v106
	v_fma_f32 v105, -v105, v108, v107
	v_div_fmas_f32 v105, v105, v106, v108
	v_div_fixup_f32 v96, v105, v104, v96
	ds_write_b32 v1, v96 offset:8192
	s_waitcnt vmcnt(6)
	v_mul_f32_e32 v104, 0xbfb8aa3b, v97
	v_exp_f32_e32 v104, v104
	s_nop 0
	v_add_f32_e32 v104, 1.0, v104
	v_div_scale_f32 v105, s[54:55], v104, v104, v97
	v_rcp_f32_e32 v106, v105
	v_div_scale_f32 v107, vcc, v97, v104, v97
	v_fma_f32 v108, -v105, v106, 1.0
	v_fmac_f32_e32 v106, v108, v106
	v_mul_f32_e32 v108, v107, v106
	v_fma_f32 v109, -v105, v108, v107
	v_fmac_f32_e32 v108, v109, v106
	v_fma_f32 v105, -v105, v108, v107
	v_div_fmas_f32 v105, v105, v106, v108
	v_div_fixup_f32 v97, v105, v104, v97
	ds_write_b32 v1, v97 offset:8448
	s_waitcnt vmcnt(5)
	v_mul_f32_e32 v104, 0xbfb8aa3b, v98
	v_exp_f32_e32 v104, v104
	s_nop 0
	v_add_f32_e32 v104, 1.0, v104
	v_div_scale_f32 v105, s[54:55], v104, v104, v98
	v_rcp_f32_e32 v106, v105
	v_div_scale_f32 v107, vcc, v98, v104, v98
	v_fma_f32 v108, -v105, v106, 1.0
	v_fmac_f32_e32 v106, v108, v106
	v_mul_f32_e32 v108, v107, v106
	v_fma_f32 v109, -v105, v108, v107
	v_fmac_f32_e32 v108, v109, v106
	v_fma_f32 v105, -v105, v108, v107
	v_div_fmas_f32 v105, v105, v106, v108
	v_div_fixup_f32 v98, v105, v104, v98
	ds_write_b32 v1, v98 offset:8704
	s_waitcnt vmcnt(4)
	v_mul_f32_e32 v104, 0xbfb8aa3b, v99
	v_exp_f32_e32 v104, v104
	s_nop 0
	v_add_f32_e32 v104, 1.0, v104
	v_div_scale_f32 v105, s[54:55], v104, v104, v99
	v_rcp_f32_e32 v106, v105
	v_div_scale_f32 v107, vcc, v99, v104, v99
	v_fma_f32 v108, -v105, v106, 1.0
	v_fmac_f32_e32 v106, v108, v106
	v_mul_f32_e32 v108, v107, v106
	v_fma_f32 v109, -v105, v108, v107
	v_fmac_f32_e32 v108, v109, v106
	v_fma_f32 v105, -v105, v108, v107
	v_div_fmas_f32 v105, v105, v106, v108
	v_div_fixup_f32 v99, v105, v104, v99
	ds_write_b32 v1, v99 offset:8960
	s_waitcnt vmcnt(3)
	v_mul_f32_e32 v104, 0xbfb8aa3b, v100
	v_exp_f32_e32 v104, v104
	s_nop 0
	v_add_f32_e32 v104, 1.0, v104
	v_div_scale_f32 v105, s[54:55], v104, v104, v100
	v_rcp_f32_e32 v106, v105
	v_div_scale_f32 v107, vcc, v100, v104, v100
	v_fma_f32 v108, -v105, v106, 1.0
	v_fmac_f32_e32 v106, v108, v106
	v_mul_f32_e32 v108, v107, v106
	v_fma_f32 v109, -v105, v108, v107
	v_fmac_f32_e32 v108, v109, v106
	v_fma_f32 v105, -v105, v108, v107
	v_div_fmas_f32 v105, v105, v106, v108
	v_div_fixup_f32 v100, v105, v104, v100
	ds_write_b32 v1, v100 offset:9216
	s_waitcnt vmcnt(2)
	v_mul_f32_e32 v104, 0xbfb8aa3b, v101
	v_exp_f32_e32 v104, v104
	s_nop 0
	v_add_f32_e32 v104, 1.0, v104
	v_div_scale_f32 v105, s[54:55], v104, v104, v101
	v_rcp_f32_e32 v106, v105
	v_div_scale_f32 v107, vcc, v101, v104, v101
	v_fma_f32 v108, -v105, v106, 1.0
	v_fmac_f32_e32 v106, v108, v106
	v_mul_f32_e32 v108, v107, v106
	v_fma_f32 v109, -v105, v108, v107
	v_fmac_f32_e32 v108, v109, v106
	v_fma_f32 v105, -v105, v108, v107
	v_div_fmas_f32 v105, v105, v106, v108
	v_div_fixup_f32 v101, v105, v104, v101
	ds_write_b32 v1, v101 offset:9472
	s_waitcnt vmcnt(1)
	v_mul_f32_e32 v104, 0xbfb8aa3b, v102
	v_exp_f32_e32 v104, v104
	s_nop 0
	v_add_f32_e32 v104, 1.0, v104
	v_div_scale_f32 v105, s[54:55], v104, v104, v102
	v_rcp_f32_e32 v106, v105
	v_div_scale_f32 v107, vcc, v102, v104, v102
	v_fma_f32 v108, -v105, v106, 1.0
	v_fmac_f32_e32 v106, v108, v106
	v_mul_f32_e32 v108, v107, v106
	v_fma_f32 v109, -v105, v108, v107
	v_fmac_f32_e32 v108, v109, v106
	v_fma_f32 v105, -v105, v108, v107
	v_div_fmas_f32 v105, v105, v106, v108
	v_div_fixup_f32 v102, v105, v104, v102
	ds_write_b32 v1, v102 offset:9728
	s_waitcnt vmcnt(0)
	v_mul_f32_e32 v104, 0xbfb8aa3b, v103
	v_exp_f32_e32 v104, v104
	s_nop 0
	v_add_f32_e32 v104, 1.0, v104
	v_div_scale_f32 v105, s[54:55], v104, v104, v103
	v_rcp_f32_e32 v106, v105
	v_div_scale_f32 v107, vcc, v103, v104, v103
	v_fma_f32 v108, -v105, v106, 1.0
	v_fmac_f32_e32 v106, v108, v106
	v_mul_f32_e32 v108, v107, v106
	v_fma_f32 v109, -v105, v108, v107
	v_fmac_f32_e32 v108, v109, v106
	v_fma_f32 v105, -v105, v108, v107
	v_div_fmas_f32 v105, v105, v106, v108
	v_div_fixup_f32 v103, v105, v104, v103
	ds_write_b32 v1, v103 offset:9984
	s_waitcnt lgkmcnt(0)
	s_load_dwordx2 s[38:39], s[26:27], 0x48
	s_mov_b32 s37, -4
	s_waitcnt lgkmcnt(0)
	v_lshl_add_u64 v[48:49], s[38:39], 0, v[4:5]
	v_lshl_add_u64 v[48:49], v[48:49], 0, s[30:31]
	v_mad_i64_i32 v[48:49], s[38:39], s36, v62, v[48:49]
	s_mov_b32 s36, s9
	v_add_co_u32_e32 v52, vcc, s44, v48
	global_load_dword v50, v[48:49], off
	s_nop 0
	v_addc_co_u32_e32 v53, vcc, -1, v49, vcc
	v_add_co_u32_e32 v54, vcc, s45, v48
	s_nop 1
	v_addc_co_u32_e32 v55, vcc, -1, v49, vcc
	v_add_co_u32_e32 v56, vcc, s46, v48
	s_nop 1
	v_addc_co_u32_e32 v57, vcc, -1, v49, vcc
	global_load_dword v222, v[52:53], off
	global_load_dword v224, v[54:55], off
	global_load_dword v226, v[56:57], off
.LBB0_128:
	v_mov_b32_e32 v51, s36
	s_add_i32 s37, s37, 4
	ds_read_b128 v[52:55], v51
	ds_read_b128 v[64:67], v51 offset:256
	ds_read_b128 v[68:71], v51 offset:512
	ds_read_b128 v[72:75], v51 offset:768
	ds_read_b128 v[76:79], v51 offset:1024
	ds_read_b128 v[80:83], v51 offset:1280
	ds_read_b128 v[84:87], v51 offset:1536
	ds_read_b128 v[88:91], v51 offset:1792
	ds_read_b128 v[92:95], v51 offset:2048
	ds_read_b128 v[96:99], v51 offset:2304
	ds_read_b128 v[100:103], v51 offset:2560
	ds_read_b128 v[104:107], v51 offset:2816
	ds_read_b128 v[108:111], v51 offset:3072
	ds_read_b128 v[112:115], v51 offset:3328
	ds_read_b128 v[116:119], v51 offset:3584
	ds_read_b128 v[120:123], v51 offset:3840
	ds_read_b128 v[124:127], v51 offset:4096
	ds_read_b128 v[128:131], v51 offset:4352
	ds_read_b128 v[132:135], v51 offset:4608
	ds_read_b128 v[136:139], v51 offset:4864
	ds_read_b128 v[140:143], v51 offset:5120
	ds_read_b128 v[144:147], v51 offset:5376
	ds_read_b128 v[148:151], v51 offset:5632
	ds_read_b128 v[152:155], v51 offset:5888
	ds_read_b128 v[156:159], v51 offset:6144
	ds_read_b128 v[160:163], v51 offset:6400
	ds_read_b128 v[164:167], v51 offset:6656
	ds_read_b128 v[168:171], v51 offset:6912
	ds_read_b128 v[172:175], v51 offset:7168
	ds_read_b128 v[176:179], v51 offset:7424
	ds_read_b128 v[182:185], v51 offset:7680
	ds_read_b128 v[186:189], v51 offset:7936
	ds_read_b128 v[190:193], v51 offset:8192
	ds_read_b128 v[194:197], v51 offset:8448
	ds_read_b128 v[198:201], v51 offset:8704
	ds_read_b128 v[202:205], v51 offset:8960
	ds_read_b128 v[206:209], v51 offset:9216
	ds_read_b128 v[210:213], v51 offset:9472
	ds_read_b128 v[214:217], v51 offset:9728
	ds_read_b128 v[218:221], v51 offset:9984
	s_waitcnt vmcnt(0)
	v_mov_b32_e32 v228, v222
	v_mov_b32_e32 v229, v224
	v_mov_b32_e32 v230, v226
	v_mov_b32_e32 v231, v50
	v_lshl_add_u64 v[48:49], v[48:49], 0, s[4:5]
	s_cmp_gt_u32 s37, 59
	s_cbranch_scc1 .Lgk_nopf
	v_add_co_u32_e32 v232, vcc, s44, v48
	global_load_dword v50, v[48:49], off
	s_nop 0
	v_addc_co_u32_e32 v233, vcc, -1, v49, vcc
	v_add_co_u32_e32 v234, vcc, s45, v48
	s_nop 1
	v_addc_co_u32_e32 v235, vcc, -1, v49, vcc
	v_add_co_u32_e32 v236, vcc, s46, v48
	s_nop 1
	v_addc_co_u32_e32 v237, vcc, -1, v49, vcc
	global_load_dword v222, v[232:233], off
	global_load_dword v224, v[234:235], off
	global_load_dword v226, v[236:237], off
.Lgk_nopf:
	s_waitcnt lgkmcnt(15)
	v_fmac_f32_e32 v47, v52, v228
	v_fmac_f32_e32 v47, v53, v229
	v_fmac_f32_e32 v47, v54, v230
	v_fmac_f32_e32 v47, v55, v231
	v_fmac_f32_e32 v46, v64, v228
	v_fmac_f32_e32 v46, v65, v229
	v_fmac_f32_e32 v46, v66, v230
	v_fmac_f32_e32 v46, v67, v231
	v_fmac_f32_e32 v45, v68, v228
	v_fmac_f32_e32 v45, v69, v229
	v_fmac_f32_e32 v45, v70, v230
	v_fmac_f32_e32 v45, v71, v231
	v_fmac_f32_e32 v44, v72, v228
	v_fmac_f32_e32 v44, v73, v229
	v_fmac_f32_e32 v44, v74, v230
	v_fmac_f32_e32 v44, v75, v231
	v_fmac_f32_e32 v43, v76, v228
	v_fmac_f32_e32 v43, v77, v229
	v_fmac_f32_e32 v43, v78, v230
	v_fmac_f32_e32 v43, v79, v231
	v_fmac_f32_e32 v42, v80, v228
	v_fmac_f32_e32 v42, v81, v229
	v_fmac_f32_e32 v42, v82, v230
	v_fmac_f32_e32 v42, v83, v231
	v_fmac_f32_e32 v41, v84, v228
	v_fmac_f32_e32 v41, v85, v229
	v_fmac_f32_e32 v41, v86, v230
	v_fmac_f32_e32 v41, v87, v231
	v_fmac_f32_e32 v40, v88, v228
	v_fmac_f32_e32 v40, v89, v229
	v_fmac_f32_e32 v40, v90, v230
	v_fmac_f32_e32 v40, v91, v231
	v_fmac_f32_e32 v39, v92, v228
	v_fmac_f32_e32 v39, v93, v229
	v_fmac_f32_e32 v39, v94, v230
	v_fmac_f32_e32 v39, v95, v231
	v_fmac_f32_e32 v38, v96, v228
	v_fmac_f32_e32 v38, v97, v229
	v_fmac_f32_e32 v38, v98, v230
	v_fmac_f32_e32 v38, v99, v231
	v_fmac_f32_e32 v37, v100, v228
	v_fmac_f32_e32 v37, v101, v229
	v_fmac_f32_e32 v37, v102, v230
	v_fmac_f32_e32 v37, v103, v231
	v_fmac_f32_e32 v36, v104, v228
	v_fmac_f32_e32 v36, v105, v229
	v_fmac_f32_e32 v36, v106, v230
	v_fmac_f32_e32 v36, v107, v231
	v_fmac_f32_e32 v35, v108, v228
	v_fmac_f32_e32 v35, v109, v229
	v_fmac_f32_e32 v35, v110, v230
	v_fmac_f32_e32 v35, v111, v231
	v_fmac_f32_e32 v34, v112, v228
	v_fmac_f32_e32 v34, v113, v229
	v_fmac_f32_e32 v34, v114, v230
	v_fmac_f32_e32 v34, v115, v231
	v_fmac_f32_e32 v33, v116, v228
	v_fmac_f32_e32 v33, v117, v229
	v_fmac_f32_e32 v33, v118, v230
	v_fmac_f32_e32 v33, v119, v231
	v_fmac_f32_e32 v32, v120, v228
	v_fmac_f32_e32 v32, v121, v229
	v_fmac_f32_e32 v32, v122, v230
	v_fmac_f32_e32 v32, v123, v231
	v_fmac_f32_e32 v31, v124, v228
	v_fmac_f32_e32 v31, v125, v229
	v_fmac_f32_e32 v31, v126, v230
	v_fmac_f32_e32 v31, v127, v231
	v_fmac_f32_e32 v30, v128, v228
	v_fmac_f32_e32 v30, v129, v229
	v_fmac_f32_e32 v30, v130, v230
	v_fmac_f32_e32 v30, v131, v231
	v_fmac_f32_e32 v29, v132, v228
	v_fmac_f32_e32 v29, v133, v229
	v_fmac_f32_e32 v29, v134, v230
	v_fmac_f32_e32 v29, v135, v231
	v_fmac_f32_e32 v28, v136, v228
	v_fmac_f32_e32 v28, v137, v229
	v_fmac_f32_e32 v28, v138, v230
	v_fmac_f32_e32 v28, v139, v231
	v_fmac_f32_e32 v27, v140, v228
	v_fmac_f32_e32 v27, v141, v229
	v_fmac_f32_e32 v27, v142, v230
	v_fmac_f32_e32 v27, v143, v231
	v_fmac_f32_e32 v26, v144, v228
	v_fmac_f32_e32 v26, v145, v229
	v_fmac_f32_e32 v26, v146, v230
	v_fmac_f32_e32 v26, v147, v231
	v_fmac_f32_e32 v25, v148, v228
	v_fmac_f32_e32 v25, v149, v229
	v_fmac_f32_e32 v25, v150, v230
	v_fmac_f32_e32 v25, v151, v231
	v_fmac_f32_e32 v24, v152, v228
	v_fmac_f32_e32 v24, v153, v229
	v_fmac_f32_e32 v24, v154, v230
	v_fmac_f32_e32 v24, v155, v231
	v_fmac_f32_e32 v23, v156, v228
	v_fmac_f32_e32 v23, v157, v229
	v_fmac_f32_e32 v23, v158, v230
	v_fmac_f32_e32 v23, v159, v231
	s_waitcnt lgkmcnt(14)
	v_fmac_f32_e32 v22, v160, v228
	v_fmac_f32_e32 v22, v161, v229
	v_fmac_f32_e32 v22, v162, v230
	v_fmac_f32_e32 v22, v163, v231
	s_waitcnt lgkmcnt(13)
	v_fmac_f32_e32 v21, v164, v228
	v_fmac_f32_e32 v21, v165, v229
	v_fmac_f32_e32 v21, v166, v230
	v_fmac_f32_e32 v21, v167, v231
	s_waitcnt lgkmcnt(12)
	v_fmac_f32_e32 v20, v168, v228
	v_fmac_f32_e32 v20, v169, v229
	v_fmac_f32_e32 v20, v170, v230
	v_fmac_f32_e32 v20, v171, v231
	s_waitcnt lgkmcnt(11)
	v_fmac_f32_e32 v19, v172, v228
	v_fmac_f32_e32 v19, v173, v229
	v_fmac_f32_e32 v19, v174, v230
	v_fmac_f32_e32 v19, v175, v231
	s_waitcnt lgkmcnt(10)
	v_fmac_f32_e32 v18, v176, v228
	v_fmac_f32_e32 v18, v177, v229
	v_fmac_f32_e32 v18, v178, v230
	v_fmac_f32_e32 v18, v179, v231
	s_waitcnt lgkmcnt(9)
	v_fmac_f32_e32 v17, v182, v228
	v_fmac_f32_e32 v17, v183, v229
	v_fmac_f32_e32 v17, v184, v230
	v_fmac_f32_e32 v17, v185, v231
	s_waitcnt lgkmcnt(8)
	v_fmac_f32_e32 v16, v186, v228
	v_fmac_f32_e32 v16, v187, v229
	v_fmac_f32_e32 v16, v188, v230
	v_fmac_f32_e32 v16, v189, v231
	s_waitcnt lgkmcnt(7)
	v_fmac_f32_e32 v15, v190, v228
	v_fmac_f32_e32 v15, v191, v229
	v_fmac_f32_e32 v15, v192, v230
	v_fmac_f32_e32 v15, v193, v231
	s_waitcnt lgkmcnt(6)
	v_fmac_f32_e32 v14, v194, v228
	v_fmac_f32_e32 v14, v195, v229
	v_fmac_f32_e32 v14, v196, v230
	v_fmac_f32_e32 v14, v197, v231
	s_waitcnt lgkmcnt(5)
	v_fmac_f32_e32 v13, v198, v228
	v_fmac_f32_e32 v13, v199, v229
	v_fmac_f32_e32 v13, v200, v230
	v_fmac_f32_e32 v13, v201, v231
	s_waitcnt lgkmcnt(4)
	v_fmac_f32_e32 v12, v202, v228
	v_fmac_f32_e32 v12, v203, v229
	v_fmac_f32_e32 v12, v204, v230
	v_fmac_f32_e32 v12, v205, v231
	s_waitcnt lgkmcnt(3)
	v_fmac_f32_e32 v11, v206, v228
	v_fmac_f32_e32 v11, v207, v229
	v_fmac_f32_e32 v11, v208, v230
	v_fmac_f32_e32 v11, v209, v231
	s_waitcnt lgkmcnt(2)
	v_fmac_f32_e32 v10, v210, v228
	v_fmac_f32_e32 v10, v211, v229
	v_fmac_f32_e32 v10, v212, v230
	v_fmac_f32_e32 v10, v213, v231
	s_waitcnt lgkmcnt(1)
	v_fmac_f32_e32 v9, v214, v228
	v_fmac_f32_e32 v9, v215, v229
	v_fmac_f32_e32 v9, v216, v230
	v_fmac_f32_e32 v9, v217, v231
	s_waitcnt lgkmcnt(0)
	v_fmac_f32_e32 v8, v218, v228
	v_fmac_f32_e32 v8, v219, v229
	v_fmac_f32_e32 v8, v220, v230
	v_fmac_f32_e32 v8, v221, v231
	s_add_i32 s36, s36, 16
	s_cmp_gt_u32 s37, 59
	s_cbranch_scc0 .LBB0_128
	s_waitcnt lgkmcnt(0)
	s_movk_i32 s38, 0x200
	s_mov_b64 s[36:37], 0
	s_and_b64 vcc, exec, s[34:35]
	s_cbranch_vccz .LBB0_121
	s_barrier
	ds_write2st64_b32 v61, v47, v46 offset1:1
	ds_write2st64_b32 v61, v45, v44 offset0:2 offset1:3
	ds_write2st64_b32 v61, v43, v42 offset0:4 offset1:5
	ds_write2st64_b32 v61, v41, v40 offset0:6 offset1:7
	ds_write2st64_b32 v61, v39, v38 offset0:8 offset1:9
	ds_write2st64_b32 v61, v37, v36 offset0:10 offset1:11
	ds_write2st64_b32 v61, v35, v34 offset0:12 offset1:13
	ds_write2st64_b32 v61, v33, v32 offset0:14 offset1:15
	ds_write2st64_b32 v61, v31, v30 offset0:16 offset1:17
	ds_write2st64_b32 v61, v29, v28 offset0:18 offset1:19
	ds_write2st64_b32 v61, v27, v26 offset0:20 offset1:21
	ds_write2st64_b32 v61, v25, v24 offset0:22 offset1:23
	ds_write2st64_b32 v61, v23, v22 offset0:24 offset1:25
	ds_write2st64_b32 v61, v21, v20 offset0:26 offset1:27
	ds_write2st64_b32 v61, v19, v18 offset0:28 offset1:29
	ds_write2st64_b32 v61, v17, v16 offset0:30 offset1:31
	ds_write2st64_b32 v61, v15, v14 offset0:32 offset1:33
	ds_write2st64_b32 v61, v13, v12 offset0:34 offset1:35
	ds_write2st64_b32 v61, v11, v10 offset0:36 offset1:37
	ds_write2st64_b32 v61, v9, v8 offset0:38 offset1:39
	s_waitcnt lgkmcnt(0)
	s_barrier
	s_load_dwordx2 s[30:31], s[26:27], 0x50
	s_mul_i32 s35, s47, 0x3000
	s_mul_hi_i32 s34, s47, 0x3000
	v_mov_b32_e32 v12, v60
	v_mov_b32_e32 v13, v59
	s_waitcnt lgkmcnt(0)
	s_add_u32 s30, s30, s35
	s_addc_u32 s31, s31, s34
	s_add_u32 s30, s30, s28
	s_addc_u32 s31, s31, s29
	v_lshl_add_u64 v[8:9], s[30:31], 0, v[2:3]
	s_mul_i32 s31, s47, 0x78000
	s_mul_hi_i32 s30, s47, 0x78000
	s_add_u32 s28, s31, s28
	s_addc_u32 s29, s30, s29
	v_lshl_add_u64 v[10:11], v[6:7], 0, s[28:29]
	s_mov_b64 s[28:29], 0

.LBB0_140:
	s_andn2_saveexec_b64 s[6:7], s[38:39]
	s_cbranch_execz .LBB0_135
	v_ashrrev_i32_e32 v7, 31, v6
	s_load_dwordx4 s[44:47], s[26:27], 0x10
	v_lshlrev_b64 v[6:7], 19, v[6:7]
	v_lshlrev_b64 v[4:5], 10, v[4:5]
	v_lshl_add_u64 v[4:5], v[6:7], 0, v[4:5]
	v_or_b32_e32 v4, v4, v10
	v_lshlrev_b64 v[14:15], 2, v[4:5]
	s_waitcnt lgkmcnt(0)
	v_lshl_add_u64 v[16:17], s[44:45], 0, v[14:15]
	v_lshl_add_u64 v[14:15], s[46:47], 0, v[14:15]
	global_load_dwordx4 v[4:7], v[16:17], off
	global_load_dwordx4 v[10:13], v[16:17], off offset:16
	global_load_dwordx4 v[18:21], v[14:15], off
	global_load_dwordx4 v[14:17], v[14:15], off offset:16
	v_lshlrev_b64 v[2:3], 1, v[2:3]
	s_waitcnt vmcnt(3)
	v_cvt_pk_bf16_f32 v4, v4, v5
	v_cvt_pk_bf16_f32 v5, v6, v7
	s_waitcnt vmcnt(2)
	v_cvt_pk_bf16_f32 v6, v10, v11
	v_cvt_pk_bf16_f32 v7, v12, v13
	v_lshl_add_u64 v[10:11], s[28:29], 0, v[2:3]
	global_store_dwordx4 v[10:11], v[4:7], off
	v_lshl_add_u64 v[2:3], s[30:31], 0, v[2:3]
	s_waitcnt vmcnt(2)
	v_cvt_pk_bf16_f32 v18, v18, v19
	v_cvt_pk_bf16_f32 v19, v20, v21
	s_waitcnt vmcnt(1)
	v_cvt_pk_bf16_f32 v20, v14, v15
	v_cvt_pk_bf16_f32 v21, v16, v17
	global_store_dwordx4 v[2:3], v[18:21], off
	s_branch .LBB0_135
